# speedup vs baseline: 1.0157x; 1.0018x over previous
.LBB0_1291:
	s_ashr_i32 s5, s4, 31
	s_and_b32 s6, s8, 0x700
	v_readlane_b32 s7, v240, 43
	s_lshl_b64 s[4:5], s[4:5], 11
	s_add_i32 s6, s6, s7
	s_add_u32 s4, s4, s6
	s_addc_u32 s5, s5, 0
	v_and_or_b32 v8, v15, 31, s4
	v_mov_b32_e32 v9, s5
	v_readlane_b32 s4, v240, 62
	v_lshlrev_b64 v[8:9], 10, v[8:9]
	v_readlane_b32 s5, v240, 63
	v_bfe_u32 v173, v172, 5, 1
	s_add_i32 s10, s10, s82
	v_lshl_add_u64 v[10:11], s[4:5], 0, v[8:9]
	v_readlane_b32 s4, v238, 54
	v_readlane_b32 s5, v238, 55
	v_lshl_add_u64 v[10:11], v[10:11], 0, s[22:23]
	s_nop 0
	v_lshl_add_u64 v[8:9], s[4:5], 0, v[8:9]
	v_lshl_add_u64 v[170:171], v[8:9], 0, s[22:23]
	v_lshlrev_b32_e32 v9, 8, v128
	v_add_u32_e32 v12, v13, v9
	s_waitcnt vmcnt(1)
	ds_write_b128 v12, v[74:77]
	v_add_u32_e32 v4, v16, v9
	s_waitcnt vmcnt(0)
	ds_write_b128 v4, v[78:81]
	v_lshlrev_b32_e32 v0, 4, v173
	v_mov_b32_e32 v1, v129
	v_lshl_add_u64 v[0:1], v[10:11], 0, v[0:1]
	global_load_dwordx4 v[112:115], v[0:1], off
	global_load_dwordx4 v[154:157], v[0:1], off offset:32
	global_load_dwordx4 v[150:153], v[0:1], off offset:64
	global_load_dwordx4 v[146:149], v[0:1], off offset:96
	global_load_dwordx4 v[142:145], v[0:1], off offset:128
	global_load_dwordx4 v[138:141], v[0:1], off offset:160
	global_load_dwordx4 v[134:137], v[0:1], off offset:192
	global_load_dwordx4 v[130:133], v[0:1], off offset:224
	v_lshlrev_b32_e32 v0, 8, v172
	v_lshrrev_b32_e32 v8, 5, v172
	v_and_b32_e32 v0, 0x1f00, v0
	v_add_u32_e32 v4, 0, v0
	v_bitop3_b32 v0, v8, v14, 1 bitop3:0x6c
	v_lshl_add_u32 v116, v0, 4, v4
	s_waitcnt lgkmcnt(0)
	s_barrier
	ds_read_b128 v[0:3], v116
	s_mov_b32 s4, 0xff800000
	v_lshlrev_b32_e32 v128, 3, v173
	s_waitcnt vmcnt(7) lgkmcnt(0)
	v_mfma_f32_32x32x16_bf16 v[48:63], v[0:3], v[112:115], 0
	v_bitop3_b32 v0, v173, v14, 2 bitop3:0x36
	v_lshl_add_u32 v164, v0, 4, v4
	ds_read_b128 v[0:3], v164
	ds_read_b128 v[64:67], v164 offset:24576
	ds_read_b128 v[80:83], v164 offset:32768
	ds_read_b128 v[96:99], v164 offset:40960
	ds_read_b128 v[118:121], v164 offset:49152
	s_waitcnt vmcnt(6) lgkmcnt(4)
	v_mfma_f32_32x32x16_bf16 v[48:63], v[0:3], v[154:157], v[48:63]
	v_bitop3_b32 v0, v173, v14, 4 bitop3:0x36
	v_lshl_add_u32 v163, v0, 4, v4
	ds_read_b128 v[0:3], v163
	s_waitcnt vmcnt(5) lgkmcnt(0)
	v_mfma_f32_32x32x16_bf16 v[48:63], v[0:3], v[150:153], v[48:63]
	v_bitop3_b32 v0, v173, v14, 6 bitop3:0x36
	v_lshl_add_u32 v162, v0, 4, v4
	ds_read_b128 v[0:3], v162
	s_waitcnt vmcnt(4) lgkmcnt(0)
	v_mfma_f32_32x32x16_bf16 v[48:63], v[0:3], v[146:149], v[48:63]
	v_bitop3_b32 v0, v173, v14, 8 bitop3:0x36
	v_lshl_add_u32 v161, v0, 4, v4
	ds_read_b128 v[0:3], v161
	s_waitcnt vmcnt(3) lgkmcnt(0)
	v_mfma_f32_32x32x16_bf16 v[48:63], v[0:3], v[142:145], v[48:63]
	v_bitop3_b32 v0, v173, v14, 10 bitop3:0x36
	v_lshl_add_u32 v160, v0, 4, v4
	ds_read_b128 v[0:3], v160
	s_waitcnt vmcnt(2) lgkmcnt(0)
	v_mfma_f32_32x32x16_bf16 v[48:63], v[0:3], v[138:141], v[48:63]
	v_bitop3_b32 v0, v173, v14, 12 bitop3:0x36
	v_lshl_add_u32 v159, v0, 4, v4
	ds_read_b128 v[0:3], v159
	s_waitcnt vmcnt(1) lgkmcnt(0)
	v_mfma_f32_32x32x16_bf16 v[48:63], v[0:3], v[134:137], v[48:63]
	v_bitop3_b32 v0, v173, v14, 14 bitop3:0x36
	v_lshl_add_u32 v158, v0, 4, v4
	ds_read_b128 v[0:3], v158
	s_waitcnt vmcnt(0) lgkmcnt(0)
	v_mfma_f32_32x32x16_bf16 v[48:63], v[0:3], v[130:133], v[48:63]
	ds_read_b128 v[0:3], v116 offset:8192
	s_waitcnt lgkmcnt(0)
	v_mfma_f32_32x32x16_bf16 v[32:47], v[0:3], v[112:115], 0
	ds_read_b128 v[0:3], v164 offset:8192
	s_waitcnt lgkmcnt(0)
	v_mfma_f32_32x32x16_bf16 v[32:47], v[0:3], v[154:157], v[32:47]
	ds_read_b128 v[0:3], v163 offset:8192
	s_waitcnt lgkmcnt(0)
	v_mfma_f32_32x32x16_bf16 v[32:47], v[0:3], v[150:153], v[32:47]
	ds_read_b128 v[0:3], v162 offset:8192
	s_waitcnt lgkmcnt(0)
	v_mfma_f32_32x32x16_bf16 v[32:47], v[0:3], v[146:149], v[32:47]
	ds_read_b128 v[0:3], v161 offset:8192
	s_waitcnt lgkmcnt(0)
	v_mfma_f32_32x32x16_bf16 v[32:47], v[0:3], v[142:145], v[32:47]
	ds_read_b128 v[0:3], v160 offset:8192
	s_waitcnt lgkmcnt(0)
	v_mfma_f32_32x32x16_bf16 v[32:47], v[0:3], v[138:141], v[32:47]
	ds_read_b128 v[0:3], v159 offset:8192
	s_waitcnt lgkmcnt(0)
	v_mfma_f32_32x32x16_bf16 v[32:47], v[0:3], v[134:137], v[32:47]
	ds_read_b128 v[0:3], v158 offset:8192
	s_waitcnt lgkmcnt(0)
	v_mfma_f32_32x32x16_bf16 v[32:47], v[0:3], v[130:133], v[32:47]
	ds_read_b128 v[0:3], v116 offset:16384
	s_waitcnt lgkmcnt(0)
	v_mfma_f32_32x32x16_bf16 v[16:31], v[0:3], v[112:115], 0
	ds_read_b128 v[0:3], v164 offset:16384
	ds_read_b128 v[164:167], v164 offset:57344
	s_waitcnt lgkmcnt(1)
	v_mfma_f32_32x32x16_bf16 v[16:31], v[0:3], v[154:157], v[16:31]
	ds_read_b128 v[0:3], v163 offset:16384
	s_waitcnt lgkmcnt(0)
	v_mfma_f32_32x32x16_bf16 v[16:31], v[0:3], v[150:153], v[16:31]
	ds_read_b128 v[0:3], v162 offset:16384
	s_waitcnt lgkmcnt(0)
	v_mfma_f32_32x32x16_bf16 v[16:31], v[0:3], v[146:149], v[16:31]
	ds_read_b128 v[0:3], v161 offset:16384
	s_waitcnt lgkmcnt(0)
	v_mfma_f32_32x32x16_bf16 v[16:31], v[0:3], v[142:145], v[16:31]
	ds_read_b128 v[0:3], v160 offset:16384
	s_waitcnt lgkmcnt(0)
	v_mfma_f32_32x32x16_bf16 v[16:31], v[0:3], v[138:141], v[16:31]
	ds_read_b128 v[0:3], v159 offset:16384
	s_waitcnt lgkmcnt(0)
	v_mfma_f32_32x32x16_bf16 v[16:31], v[0:3], v[134:137], v[16:31]
	ds_read_b128 v[0:3], v158 offset:16384
	s_waitcnt lgkmcnt(0)
	v_mfma_f32_32x32x16_bf16 v[16:31], v[0:3], v[130:133], v[16:31]
	ds_read_b128 v[0:3], v116 offset:24576
	s_waitcnt lgkmcnt(0)
	v_mfma_f32_32x32x16_bf16 v[0:15], v[0:3], v[112:115], 0
	v_mfma_f32_32x32x16_bf16 v[0:15], v[64:67], v[154:157], v[0:15]
	ds_read_b128 v[64:67], v163 offset:24576
	s_waitcnt lgkmcnt(0)
	v_mfma_f32_32x32x16_bf16 v[0:15], v[64:67], v[150:153], v[0:15]
	ds_read_b128 v[64:67], v162 offset:24576
	s_waitcnt lgkmcnt(0)
	v_mfma_f32_32x32x16_bf16 v[0:15], v[64:67], v[146:149], v[0:15]
	ds_read_b128 v[64:67], v161 offset:24576
	s_waitcnt lgkmcnt(0)
	v_mfma_f32_32x32x16_bf16 v[0:15], v[64:67], v[142:145], v[0:15]
	ds_read_b128 v[64:67], v160 offset:24576
	s_waitcnt lgkmcnt(0)
	v_mfma_f32_32x32x16_bf16 v[0:15], v[64:67], v[138:141], v[0:15]
	ds_read_b128 v[64:67], v159 offset:24576
	s_waitcnt lgkmcnt(0)
	v_mfma_f32_32x32x16_bf16 v[0:15], v[64:67], v[134:137], v[0:15]
	ds_read_b128 v[64:67], v158 offset:24576
	s_waitcnt lgkmcnt(0)
	v_mfma_f32_32x32x16_bf16 v[0:15], v[64:67], v[130:133], v[0:15]
	ds_read_b128 v[64:67], v116 offset:32768
	s_waitcnt lgkmcnt(0)
	v_mfma_f32_32x32x16_bf16 v[64:79], v[64:67], v[112:115], 0
	v_mfma_f32_32x32x16_bf16 v[64:79], v[80:83], v[154:157], v[64:79]
	ds_read_b128 v[80:83], v163 offset:32768
	s_waitcnt lgkmcnt(0)
	v_mfma_f32_32x32x16_bf16 v[64:79], v[80:83], v[150:153], v[64:79]
	ds_read_b128 v[80:83], v162 offset:32768
	s_waitcnt lgkmcnt(0)
	v_mfma_f32_32x32x16_bf16 v[64:79], v[80:83], v[146:149], v[64:79]
	ds_read_b128 v[80:83], v161 offset:32768
	s_waitcnt lgkmcnt(0)
	v_mfma_f32_32x32x16_bf16 v[64:79], v[80:83], v[142:145], v[64:79]
	ds_read_b128 v[80:83], v160 offset:32768
	s_waitcnt lgkmcnt(0)
	v_mfma_f32_32x32x16_bf16 v[64:79], v[80:83], v[138:141], v[64:79]
	ds_read_b128 v[80:83], v159 offset:32768
	s_waitcnt lgkmcnt(0)
	v_mfma_f32_32x32x16_bf16 v[64:79], v[80:83], v[134:137], v[64:79]
	ds_read_b128 v[80:83], v158 offset:32768
	s_waitcnt lgkmcnt(0)
	v_mfma_f32_32x32x16_bf16 v[64:79], v[80:83], v[130:133], v[64:79]
	ds_read_b128 v[80:83], v116 offset:40960
	s_waitcnt lgkmcnt(0)
	v_mfma_f32_32x32x16_bf16 v[80:95], v[80:83], v[112:115], 0
	v_mfma_f32_32x32x16_bf16 v[80:95], v[96:99], v[154:157], v[80:95]
	ds_read_b128 v[96:99], v163 offset:40960
	s_waitcnt lgkmcnt(0)
	v_mfma_f32_32x32x16_bf16 v[80:95], v[96:99], v[150:153], v[80:95]
	ds_read_b128 v[96:99], v162 offset:40960
	s_waitcnt lgkmcnt(0)
	v_mfma_f32_32x32x16_bf16 v[80:95], v[96:99], v[146:149], v[80:95]
	ds_read_b128 v[96:99], v161 offset:40960
	s_waitcnt lgkmcnt(0)
	v_mfma_f32_32x32x16_bf16 v[80:95], v[96:99], v[142:145], v[80:95]
	ds_read_b128 v[96:99], v160 offset:40960
	s_waitcnt lgkmcnt(0)
	v_mfma_f32_32x32x16_bf16 v[80:95], v[96:99], v[138:141], v[80:95]
	ds_read_b128 v[96:99], v159 offset:40960
	s_waitcnt lgkmcnt(0)
	v_mfma_f32_32x32x16_bf16 v[80:95], v[96:99], v[134:137], v[80:95]
	ds_read_b128 v[96:99], v158 offset:40960
	s_waitcnt lgkmcnt(0)
	v_mfma_f32_32x32x16_bf16 v[80:95], v[96:99], v[130:133], v[80:95]
	ds_read_b128 v[96:99], v116 offset:49152
	s_waitcnt lgkmcnt(0)
	v_mfma_f32_32x32x16_bf16 v[96:111], v[96:99], v[112:115], 0
	v_mfma_f32_32x32x16_bf16 v[96:111], v[118:121], v[154:157], v[96:111]
	ds_read_b128 v[118:121], v163 offset:49152
	s_waitcnt lgkmcnt(0)
	v_mfma_f32_32x32x16_bf16 v[96:111], v[118:121], v[150:153], v[96:111]
	ds_read_b128 v[118:121], v162 offset:49152
	s_waitcnt lgkmcnt(0)
	v_mfma_f32_32x32x16_bf16 v[96:111], v[118:121], v[146:149], v[96:111]
	ds_read_b128 v[118:121], v161 offset:49152
	s_waitcnt lgkmcnt(0)
	v_mfma_f32_32x32x16_bf16 v[96:111], v[118:121], v[142:145], v[96:111]
	ds_read_b128 v[118:121], v160 offset:49152
	s_waitcnt lgkmcnt(0)
	v_mfma_f32_32x32x16_bf16 v[96:111], v[118:121], v[138:141], v[96:111]
	ds_read_b128 v[118:121], v159 offset:49152
	s_waitcnt lgkmcnt(0)
	v_mfma_f32_32x32x16_bf16 v[96:111], v[118:121], v[134:137], v[96:111]
	ds_read_b128 v[118:121], v158 offset:49152
	s_waitcnt lgkmcnt(0)
	v_mfma_f32_32x32x16_bf16 v[96:111], v[118:121], v[130:133], v[96:111]
	ds_read_b128 v[116:119], v116 offset:57344
	s_waitcnt lgkmcnt(0)
	v_mfma_f32_32x32x16_bf16 v[112:127], v[116:119], v[112:115], 0
	v_mfma_f32_32x32x16_bf16 v[112:127], v[164:167], v[154:157], v[112:127]
	ds_read_b128 v[154:157], v163 offset:57344
	s_waitcnt lgkmcnt(0)
	v_mfma_f32_32x32x16_bf16 v[112:127], v[154:157], v[150:153], v[112:127]
	ds_read_b128 v[150:153], v162 offset:57344
	s_waitcnt lgkmcnt(0)
	v_mfma_f32_32x32x16_bf16 v[112:127], v[150:153], v[146:149], v[112:127]
	ds_read_b128 v[146:149], v161 offset:57344
	s_waitcnt lgkmcnt(0)
	v_mfma_f32_32x32x16_bf16 v[112:127], v[146:149], v[142:145], v[112:127]
	ds_read_b128 v[142:145], v160 offset:57344
	s_waitcnt lgkmcnt(0)
	v_mfma_f32_32x32x16_bf16 v[112:127], v[142:145], v[138:141], v[112:127]
	ds_read_b128 v[138:141], v159 offset:57344
	s_waitcnt lgkmcnt(0)
	v_mfma_f32_32x32x16_bf16 v[112:127], v[138:141], v[134:137], v[112:127]
	ds_read_b128 v[134:137], v158 offset:57344
	s_waitcnt lgkmcnt(0)
	v_mfma_f32_32x32x16_bf16 v[112:127], v[134:137], v[130:133], v[112:127]
	v_max3_f32 v130, v48, s4, v49
	v_max3_f32 v130, v130, v50, v51
	v_max3_f32 v130, v130, v52, v53
	v_max3_f32 v130, v130, v54, v55
	v_max3_f32 v130, v130, v56, v57
	v_max3_f32 v130, v130, v58, v59
	v_max3_f32 v130, v130, v60, v61
	v_max3_f32 v130, v130, v62, v63
	v_max3_f32 v130, v130, v32, v33
	v_max3_f32 v130, v130, v34, v35
	v_max3_f32 v130, v130, v36, v37
	v_max3_f32 v130, v130, v38, v39
	v_max3_f32 v130, v130, v40, v41
	v_max3_f32 v130, v130, v42, v43
	v_max3_f32 v130, v130, v44, v45
	v_max3_f32 v130, v130, v46, v47
	v_max3_f32 v130, v130, v16, v17
	v_max3_f32 v130, v130, v18, v19
	v_max3_f32 v130, v130, v20, v21
	v_max3_f32 v130, v130, v22, v23
	v_max3_f32 v130, v130, v24, v25
	v_max3_f32 v130, v130, v26, v27
	v_max3_f32 v130, v130, v28, v29
	v_max3_f32 v130, v130, v30, v31
	v_max3_f32 v130, v130, v0, v1
	v_max3_f32 v130, v130, v2, v3
	v_max3_f32 v130, v130, v4, v5
	v_max3_f32 v130, v130, v6, v7
	v_max3_f32 v130, v130, v8, v9
	v_max3_f32 v130, v130, v10, v11
	v_max3_f32 v130, v130, v12, v13
	v_max3_f32 v130, v130, v14, v15
	v_max3_f32 v130, v130, v64, v65
	v_max3_f32 v130, v130, v66, v67
	v_max3_f32 v130, v130, v68, v69
	v_max3_f32 v130, v130, v70, v71
	v_max3_f32 v130, v130, v72, v73
	v_max3_f32 v130, v130, v74, v75
	v_max3_f32 v130, v130, v76, v77
	v_max3_f32 v130, v130, v78, v79
	v_max3_f32 v130, v130, v80, v81
	v_max3_f32 v130, v130, v82, v83
	v_max3_f32 v130, v130, v84, v85
	v_max3_f32 v130, v130, v86, v87
	v_max3_f32 v130, v130, v88, v89
	v_max3_f32 v130, v130, v90, v91
	v_max3_f32 v130, v130, v92, v93
	v_max3_f32 v130, v130, v94, v95
	v_max3_f32 v130, v130, v96, v97
	v_max3_f32 v130, v130, v98, v99
	v_max3_f32 v130, v130, v100, v101
	v_max3_f32 v130, v130, v102, v103
	v_max3_f32 v130, v130, v104, v105
	v_max3_f32 v130, v130, v106, v107
	v_max3_f32 v130, v130, v108, v109
	v_max3_f32 v130, v130, v110, v111
	v_max3_f32 v130, v130, v112, v113
	v_max3_f32 v130, v130, v114, v115
	v_max3_f32 v130, v130, v116, v117
	v_max3_f32 v130, v130, v118, v119
	v_and_b32_e32 v132, 64, v214
	v_max3_f32 v130, v130, v120, v121
	v_xor_b32_e32 v131, 32, v214
	v_add_u32_e32 v132, 64, v132
	v_max3_f32 v130, v130, v122, v123
	v_cmp_lt_i32_e32 vcc, v131, v132
	v_max3_f32 v130, v130, v124, v125
	v_max3_f32 v130, v130, v126, v127
	v_cndmask_b32_e32 v131, v214, v131, vcc
	v_lshlrev_b32_e32 v174, 2, v131
	ds_bpermute_b32 v131, v174, v130
	s_waitcnt lgkmcnt(0)
	v_max_f32_e32 v131, v131, v131
	v_max_f32_e32 v175, v130, v131
	v_sub_f32_e32 v48, v48, v175
	v_exp_f32_e32 v48, v48
	v_sub_f32_e32 v49, v49, v175
	v_exp_f32_e32 v49, v49
	v_sub_f32_e32 v50, v50, v175
	v_exp_f32_e32 v50, v50
	v_sub_f32_e32 v51, v51, v175
	v_exp_f32_e32 v51, v51
	v_sub_f32_e32 v52, v52, v175
	v_add_f32_e32 v130, 0, v48
	v_exp_f32_e32 v52, v52
	v_sub_f32_e32 v53, v53, v175
	v_add_f32_e32 v130, v49, v130
	v_exp_f32_e32 v53, v53
	v_sub_f32_e32 v54, v54, v175
	v_add_f32_e32 v130, v50, v130
	v_exp_f32_e32 v54, v54
	v_sub_f32_e32 v55, v55, v175
	v_add_f32_e32 v130, v51, v130
	v_exp_f32_e32 v55, v55
	v_cvt_pk_bf16_f32 v166, v48, v49
	v_sub_f32_e32 v48, v56, v175
	v_add_f32_e32 v130, v52, v130
	v_cvt_pk_bf16_f32 v167, v50, v51
	v_exp_f32_e32 v48, v48
	v_sub_f32_e32 v50, v57, v175
	v_add_f32_e32 v130, v53, v130
	v_exp_f32_e32 v50, v50
	v_sub_f32_e32 v51, v58, v175
	v_add_f32_e32 v130, v54, v130
	v_cvt_pk_bf16_f32 v168, v52, v53
	v_exp_f32_e32 v51, v51
	v_sub_f32_e32 v52, v59, v175
	v_add_f32_e32 v130, v55, v130
	v_exp_f32_e32 v52, v52
	v_sub_f32_e32 v53, v60, v175
	v_cvt_pk_bf16_f32 v169, v54, v55
	v_add_f32_e32 v49, v48, v130
	v_exp_f32_e32 v53, v53
	v_sub_f32_e32 v54, v61, v175
	v_add_f32_e32 v49, v50, v49
	v_exp_f32_e32 v54, v54
	v_sub_f32_e32 v55, v62, v175
	v_add_f32_e32 v49, v51, v49
	v_exp_f32_e32 v55, v55
	v_sub_f32_e32 v56, v63, v175
	v_add_f32_e32 v49, v52, v49
	v_exp_f32_e32 v56, v56
	v_sub_f32_e32 v32, v32, v175
	v_add_f32_e32 v49, v53, v49
	v_exp_f32_e32 v32, v32
	v_sub_f32_e32 v33, v33, v175
	v_add_f32_e32 v49, v54, v49
	v_exp_f32_e32 v33, v33
	v_sub_f32_e32 v34, v34, v175
	v_add_f32_e32 v49, v55, v49
	v_exp_f32_e32 v34, v34
	v_sub_f32_e32 v35, v35, v175
	v_add_f32_e32 v49, v56, v49
	v_exp_f32_e32 v35, v35
	v_sub_f32_e32 v36, v36, v175
	v_cvt_pk_bf16_f32 v162, v48, v50
	v_add_f32_e32 v48, v32, v49
	v_exp_f32_e32 v36, v36
	v_sub_f32_e32 v37, v37, v175
	v_add_f32_e32 v48, v33, v48
	v_exp_f32_e32 v37, v37
	v_sub_f32_e32 v38, v38, v175
	v_add_f32_e32 v48, v34, v48
	v_exp_f32_e32 v38, v38
	v_sub_f32_e32 v39, v39, v175
	v_add_f32_e32 v48, v35, v48
	v_exp_f32_e32 v39, v39
	v_cvt_pk_bf16_f32 v158, v32, v33
	v_sub_f32_e32 v32, v40, v175
	v_add_f32_e32 v48, v36, v48
	v_cvt_pk_bf16_f32 v159, v34, v35
	v_exp_f32_e32 v32, v32
	v_sub_f32_e32 v34, v41, v175
	v_add_f32_e32 v48, v37, v48
	v_exp_f32_e32 v34, v34
	v_sub_f32_e32 v35, v42, v175
	v_add_f32_e32 v48, v38, v48
	v_cvt_pk_bf16_f32 v160, v36, v37
	v_exp_f32_e32 v35, v35
	v_sub_f32_e32 v36, v43, v175
	v_add_f32_e32 v48, v39, v48
	v_exp_f32_e32 v36, v36
	v_sub_f32_e32 v37, v44, v175
	v_cvt_pk_bf16_f32 v161, v38, v39
	v_add_f32_e32 v33, v32, v48
	v_exp_f32_e32 v37, v37
	v_sub_f32_e32 v38, v45, v175
	v_add_f32_e32 v33, v34, v33
	v_exp_f32_e32 v38, v38
	v_sub_f32_e32 v39, v46, v175
	v_add_f32_e32 v33, v35, v33
	v_exp_f32_e32 v39, v39
	v_sub_f32_e32 v40, v47, v175
	v_add_f32_e32 v33, v36, v33
	v_exp_f32_e32 v40, v40
	v_sub_f32_e32 v16, v16, v175
	v_add_f32_e32 v33, v37, v33
	v_exp_f32_e32 v16, v16
	v_sub_f32_e32 v17, v17, v175
	v_add_f32_e32 v33, v38, v33
	v_exp_f32_e32 v17, v17
	v_sub_f32_e32 v18, v18, v175
	v_add_f32_e32 v33, v39, v33
	v_exp_f32_e32 v18, v18
	v_sub_f32_e32 v19, v19, v175
	v_add_f32_e32 v33, v40, v33
	v_exp_f32_e32 v19, v19
	v_sub_f32_e32 v20, v20, v175
	v_cvt_pk_bf16_f32 v154, v32, v34
	v_add_f32_e32 v32, v16, v33
	v_exp_f32_e32 v20, v20
	v_sub_f32_e32 v21, v21, v175
	v_add_f32_e32 v32, v17, v32
	v_exp_f32_e32 v21, v21
	v_sub_f32_e32 v22, v22, v175
	v_add_f32_e32 v32, v18, v32
	v_exp_f32_e32 v22, v22
	v_sub_f32_e32 v23, v23, v175
	v_add_f32_e32 v32, v19, v32
	v_exp_f32_e32 v23, v23
	v_cvt_pk_bf16_f32 v150, v16, v17
	v_sub_f32_e32 v16, v24, v175
	v_add_f32_e32 v32, v20, v32
	v_cvt_pk_bf16_f32 v151, v18, v19
	v_exp_f32_e32 v16, v16
	v_sub_f32_e32 v18, v25, v175
	v_add_f32_e32 v32, v21, v32
	v_exp_f32_e32 v18, v18
	v_sub_f32_e32 v19, v26, v175
	v_add_f32_e32 v32, v22, v32
	v_cvt_pk_bf16_f32 v152, v20, v21
	v_exp_f32_e32 v19, v19
	v_sub_f32_e32 v20, v27, v175
	v_add_f32_e32 v32, v23, v32
	v_exp_f32_e32 v20, v20
	v_sub_f32_e32 v21, v28, v175
	v_cvt_pk_bf16_f32 v153, v22, v23
	v_add_f32_e32 v17, v16, v32
	v_exp_f32_e32 v21, v21
	v_sub_f32_e32 v22, v29, v175
	v_add_f32_e32 v17, v18, v17
	v_exp_f32_e32 v22, v22
	v_sub_f32_e32 v23, v30, v175
	v_add_f32_e32 v17, v19, v17
	v_exp_f32_e32 v23, v23
	v_sub_f32_e32 v24, v31, v175
	v_add_f32_e32 v17, v20, v17
	v_exp_f32_e32 v24, v24
	v_sub_f32_e32 v0, v0, v175
	v_add_f32_e32 v17, v21, v17
	v_exp_f32_e32 v0, v0
	v_sub_f32_e32 v1, v1, v175
	v_add_f32_e32 v17, v22, v17
	v_exp_f32_e32 v1, v1
	v_sub_f32_e32 v2, v2, v175
	v_add_f32_e32 v17, v23, v17
	v_exp_f32_e32 v2, v2
	v_sub_f32_e32 v3, v3, v175
	v_add_f32_e32 v17, v24, v17
	v_exp_f32_e32 v3, v3
	v_sub_f32_e32 v4, v4, v175
	v_cvt_pk_bf16_f32 v146, v16, v18
	v_add_f32_e32 v16, v0, v17
	v_exp_f32_e32 v4, v4
	v_sub_f32_e32 v5, v5, v175
	v_add_f32_e32 v16, v1, v16
	v_exp_f32_e32 v5, v5
	v_sub_f32_e32 v6, v6, v175
	v_add_f32_e32 v16, v2, v16
	v_exp_f32_e32 v6, v6
	v_sub_f32_e32 v7, v7, v175
	v_add_f32_e32 v16, v3, v16
	v_exp_f32_e32 v7, v7
	v_cvt_pk_bf16_f32 v142, v0, v1
	v_sub_f32_e32 v0, v8, v175
	v_add_f32_e32 v16, v4, v16
	v_cvt_pk_bf16_f32 v143, v2, v3
	v_exp_f32_e32 v0, v0
	v_sub_f32_e32 v2, v9, v175
	v_add_f32_e32 v16, v5, v16
	v_exp_f32_e32 v2, v2
	v_sub_f32_e32 v3, v10, v175
	v_add_f32_e32 v16, v6, v16
	v_cvt_pk_bf16_f32 v144, v4, v5
	v_exp_f32_e32 v3, v3
	v_sub_f32_e32 v4, v11, v175
	v_add_f32_e32 v16, v7, v16
	v_exp_f32_e32 v4, v4
	v_sub_f32_e32 v5, v12, v175
	v_cvt_pk_bf16_f32 v145, v6, v7
	v_add_f32_e32 v1, v0, v16
	v_exp_f32_e32 v5, v5
	v_sub_f32_e32 v6, v13, v175
	v_add_f32_e32 v1, v2, v1
	v_exp_f32_e32 v6, v6
	v_sub_f32_e32 v7, v14, v175
	v_add_f32_e32 v1, v3, v1
	v_exp_f32_e32 v7, v7
	v_sub_f32_e32 v8, v15, v175
	v_add_f32_e32 v1, v4, v1
	v_exp_f32_e32 v8, v8
	v_cvt_pk_bf16_f32 v138, v0, v2
	v_sub_f32_e32 v0, v64, v175
	v_add_f32_e32 v1, v5, v1
	v_exp_f32_e32 v0, v0
	v_sub_f32_e32 v2, v65, v175
	v_add_f32_e32 v1, v6, v1
	v_cvt_pk_bf16_f32 v139, v3, v4
	v_exp_f32_e32 v2, v2
	v_sub_f32_e32 v3, v66, v175
	v_add_f32_e32 v1, v7, v1
	v_exp_f32_e32 v3, v3
	v_sub_f32_e32 v4, v67, v175
	v_add_f32_e32 v1, v8, v1
	v_cvt_pk_bf16_f32 v140, v5, v6
	v_exp_f32_e32 v4, v4
	v_sub_f32_e32 v5, v68, v175
	v_add_f32_e32 v1, v0, v1
	v_exp_f32_e32 v5, v5
	v_sub_f32_e32 v6, v69, v175
	v_cvt_pk_bf16_f32 v141, v7, v8
	v_add_f32_e32 v1, v2, v1
	v_exp_f32_e32 v6, v6
	v_sub_f32_e32 v7, v70, v175
	v_add_f32_e32 v1, v3, v1
	v_exp_f32_e32 v7, v7
	v_sub_f32_e32 v8, v71, v175
	v_add_f32_e32 v1, v4, v1
	v_exp_f32_e32 v8, v8
	v_cvt_pk_bf16_f32 v134, v0, v2
	v_sub_f32_e32 v0, v72, v175
	v_add_f32_e32 v1, v5, v1
	v_exp_f32_e32 v0, v0
	v_sub_f32_e32 v2, v73, v175
	v_add_f32_e32 v1, v6, v1
	v_cvt_pk_bf16_f32 v135, v3, v4
	v_exp_f32_e32 v2, v2
	v_sub_f32_e32 v3, v74, v175
	v_add_f32_e32 v1, v7, v1
	v_exp_f32_e32 v3, v3
	v_sub_f32_e32 v4, v75, v175
	v_add_f32_e32 v1, v8, v1
	v_cvt_pk_bf16_f32 v136, v5, v6
	v_exp_f32_e32 v4, v4
	v_sub_f32_e32 v5, v76, v175
	v_add_f32_e32 v1, v0, v1
	v_exp_f32_e32 v5, v5
	v_sub_f32_e32 v6, v77, v175
	v_cvt_pk_bf16_f32 v137, v7, v8
	v_add_f32_e32 v1, v2, v1
	v_exp_f32_e32 v6, v6
	v_sub_f32_e32 v7, v78, v175
	v_add_f32_e32 v1, v3, v1
	v_exp_f32_e32 v7, v7
	v_sub_f32_e32 v8, v79, v175
	v_add_f32_e32 v1, v4, v1
	v_exp_f32_e32 v8, v8
	v_cvt_pk_bf16_f32 v130, v0, v2
	v_sub_f32_e32 v0, v80, v175
	v_add_f32_e32 v1, v5, v1
	v_exp_f32_e32 v0, v0
	v_sub_f32_e32 v2, v81, v175
	v_add_f32_e32 v1, v6, v1
	v_cvt_pk_bf16_f32 v131, v3, v4
	v_exp_f32_e32 v2, v2
	v_sub_f32_e32 v3, v82, v175
	v_add_f32_e32 v1, v7, v1
	v_exp_f32_e32 v3, v3
	v_sub_f32_e32 v4, v83, v175
	v_add_f32_e32 v1, v8, v1
	v_cvt_pk_bf16_f32 v132, v5, v6
	v_exp_f32_e32 v4, v4
	v_sub_f32_e32 v5, v84, v175
	v_add_f32_e32 v1, v0, v1
	v_exp_f32_e32 v5, v5
	v_sub_f32_e32 v6, v85, v175
	v_cvt_pk_bf16_f32 v133, v7, v8
	v_add_f32_e32 v1, v2, v1
	v_exp_f32_e32 v6, v6
	v_sub_f32_e32 v7, v86, v175
	v_add_f32_e32 v1, v3, v1
	v_exp_f32_e32 v7, v7
	v_sub_f32_e32 v8, v87, v175
	v_add_f32_e32 v1, v4, v1
	v_exp_f32_e32 v8, v8
	v_cvt_pk_bf16_f32 v84, v0, v2
	v_sub_f32_e32 v0, v88, v175
	v_add_f32_e32 v1, v5, v1
	v_exp_f32_e32 v0, v0
	v_sub_f32_e32 v2, v89, v175
	v_add_f32_e32 v1, v6, v1
	v_cvt_pk_bf16_f32 v85, v3, v4
	v_exp_f32_e32 v2, v2
	v_sub_f32_e32 v3, v90, v175
	v_add_f32_e32 v1, v7, v1
	v_exp_f32_e32 v3, v3
	v_sub_f32_e32 v4, v91, v175
	v_add_f32_e32 v1, v8, v1
	v_cvt_pk_bf16_f32 v86, v5, v6
	v_exp_f32_e32 v4, v4
	v_sub_f32_e32 v5, v92, v175
	v_add_f32_e32 v1, v0, v1
	v_exp_f32_e32 v5, v5
	v_sub_f32_e32 v6, v93, v175
	v_cvt_pk_bf16_f32 v87, v7, v8
	v_add_f32_e32 v1, v2, v1
	v_exp_f32_e32 v6, v6
	v_sub_f32_e32 v7, v94, v175
	v_add_f32_e32 v1, v3, v1
	v_exp_f32_e32 v7, v7
	v_sub_f32_e32 v8, v95, v175
	v_add_f32_e32 v1, v4, v1
	v_exp_f32_e32 v8, v8
	v_cvt_pk_bf16_f32 v80, v0, v2
	v_sub_f32_e32 v0, v96, v175
	v_add_f32_e32 v1, v5, v1
	v_exp_f32_e32 v0, v0
	v_sub_f32_e32 v2, v97, v175
	v_add_f32_e32 v1, v6, v1
	v_cvt_pk_bf16_f32 v81, v3, v4
	v_exp_f32_e32 v2, v2
	v_sub_f32_e32 v3, v98, v175
	v_add_f32_e32 v1, v7, v1
	v_exp_f32_e32 v3, v3
	v_sub_f32_e32 v4, v99, v175
	v_add_f32_e32 v1, v8, v1
	v_cvt_pk_bf16_f32 v82, v5, v6
	v_exp_f32_e32 v4, v4
	v_sub_f32_e32 v5, v100, v175
	v_add_f32_e32 v1, v0, v1
	v_exp_f32_e32 v5, v5
	v_sub_f32_e32 v6, v101, v175
	v_cvt_pk_bf16_f32 v83, v7, v8
	v_add_f32_e32 v1, v2, v1
	v_exp_f32_e32 v6, v6
	v_sub_f32_e32 v7, v102, v175
	v_add_f32_e32 v1, v3, v1
	v_exp_f32_e32 v7, v7
	v_sub_f32_e32 v8, v103, v175
	v_add_f32_e32 v1, v4, v1
	v_exp_f32_e32 v8, v8
	v_cvt_pk_bf16_f32 v76, v0, v2
	v_sub_f32_e32 v0, v104, v175
	v_add_f32_e32 v1, v5, v1
	v_exp_f32_e32 v0, v0
	v_sub_f32_e32 v2, v105, v175
	v_add_f32_e32 v1, v6, v1
	v_cvt_pk_bf16_f32 v77, v3, v4
	v_exp_f32_e32 v2, v2
	v_sub_f32_e32 v3, v106, v175
	v_add_f32_e32 v1, v7, v1
	v_exp_f32_e32 v3, v3
	v_sub_f32_e32 v4, v107, v175
	v_add_f32_e32 v1, v8, v1
	v_cvt_pk_bf16_f32 v78, v5, v6
	v_exp_f32_e32 v4, v4
	v_sub_f32_e32 v5, v108, v175
	v_add_f32_e32 v1, v0, v1
	v_exp_f32_e32 v5, v5
	v_sub_f32_e32 v6, v109, v175
	v_cvt_pk_bf16_f32 v79, v7, v8
	v_add_f32_e32 v1, v2, v1
	v_exp_f32_e32 v6, v6
	v_sub_f32_e32 v7, v110, v175
	v_add_f32_e32 v1, v3, v1
	v_exp_f32_e32 v7, v7
	v_sub_f32_e32 v8, v111, v175
	v_add_f32_e32 v1, v4, v1
	v_exp_f32_e32 v8, v8
	v_cvt_pk_bf16_f32 v68, v0, v2
	v_sub_f32_e32 v0, v112, v175
	v_add_f32_e32 v1, v5, v1
	v_exp_f32_e32 v0, v0
	v_sub_f32_e32 v2, v113, v175
	v_add_f32_e32 v1, v6, v1
	v_cvt_pk_bf16_f32 v69, v3, v4
	v_exp_f32_e32 v2, v2
	v_sub_f32_e32 v3, v114, v175
	v_add_f32_e32 v1, v7, v1
	v_exp_f32_e32 v3, v3
	v_sub_f32_e32 v4, v115, v175
	v_add_f32_e32 v1, v8, v1
	v_cvt_pk_bf16_f32 v70, v5, v6
	v_exp_f32_e32 v4, v4
	v_sub_f32_e32 v5, v116, v175
	v_add_f32_e32 v1, v0, v1
	v_exp_f32_e32 v5, v5
	v_sub_f32_e32 v6, v117, v175
	v_cvt_pk_bf16_f32 v71, v7, v8
	v_add_f32_e32 v1, v2, v1
	v_exp_f32_e32 v6, v6
	v_sub_f32_e32 v7, v118, v175
	v_add_f32_e32 v1, v3, v1
	v_exp_f32_e32 v7, v7
	v_sub_f32_e32 v8, v119, v175
	v_add_f32_e32 v1, v4, v1
	v_exp_f32_e32 v8, v8
	v_cvt_pk_bf16_f32 v72, v0, v2
	v_sub_f32_e32 v0, v120, v175
	v_add_f32_e32 v1, v5, v1
	v_exp_f32_e32 v0, v0
	v_sub_f32_e32 v2, v121, v175
	v_add_f32_e32 v1, v6, v1
	v_cvt_pk_bf16_f32 v73, v3, v4
	v_exp_f32_e32 v2, v2
	v_sub_f32_e32 v3, v122, v175
	v_add_f32_e32 v1, v7, v1
	v_exp_f32_e32 v3, v3
	v_sub_f32_e32 v4, v123, v175
	v_add_f32_e32 v1, v8, v1
	v_cvt_pk_bf16_f32 v74, v5, v6
	v_exp_f32_e32 v4, v4
	v_sub_f32_e32 v5, v124, v175
	v_add_f32_e32 v1, v0, v1
	v_exp_f32_e32 v5, v5
	v_sub_f32_e32 v6, v125, v175
	v_cvt_pk_bf16_f32 v75, v7, v8
	v_add_f32_e32 v1, v2, v1
	v_exp_f32_e32 v6, v6
	v_sub_f32_e32 v7, v126, v175
	v_add_f32_e32 v1, v3, v1
	v_exp_f32_e32 v7, v7
	v_sub_f32_e32 v8, v127, v175
	v_add_f32_e32 v1, v4, v1
	v_exp_f32_e32 v8, v8
	v_add_f32_e32 v1, v5, v1
	v_add_f32_e32 v1, v6, v1
	v_add_f32_e32 v1, v7, v1
	v_add_f32_e32 v88, v8, v1
	v_cvt_pk_bf16_f32 v64, v0, v2
	v_bfe_u32 v0, v172, 2, 2
	v_lshlrev_b32_e32 v1, 1, v172
	v_cvt_pk_bf16_f32 v65, v3, v4
	v_cvt_pk_bf16_f32 v66, v5, v6
	v_lshlrev_b32_e32 v4, 6, v0
	v_and_b32_e32 v5, 32, v1
	v_lshlrev_b32_e32 v1, 3, v172
	v_lshlrev_b32_e32 v0, 8, v0
	v_and_b32_e32 v1, 24, v1
	v_lshl_or_b32 v0, v173, 10, v0
	v_or_b32_e32 v2, v4, v5
	v_add3_u32 v6, s11, v1, v0
	v_add_u32_e32 v92, v6, v2
	ds_read_b64_tr_b16 v[0:1], v92
	ds_read_b64_tr_b16 v[2:3], v92 offset:2048
	v_cvt_pk_bf16_f32 v163, v51, v52
	v_cvt_pk_bf16_f32 v164, v53, v54
	v_cvt_pk_bf16_f32 v165, v55, v56
	s_waitcnt lgkmcnt(0)
	v_mfma_f32_32x32x16_bf16 v[48:63], v[0:3], v[166:169], 0
	v_or_b32_e32 v0, 64, v5
	v_xad_u32 v93, v0, v4, v6
	ds_read_b64_tr_b16 v[0:1], v93
	ds_read_b64_tr_b16 v[2:3], v93 offset:2048
	v_cvt_pk_bf16_f32 v155, v35, v36
	v_cvt_pk_bf16_f32 v156, v37, v38
	v_cvt_pk_bf16_f32 v157, v39, v40
	v_cvt_pk_bf16_f32 v147, v19, v20
	s_waitcnt lgkmcnt(0)
	v_mfma_f32_32x32x16_bf16 v[32:47], v[0:3], v[166:169], 0
	v_or_b32_e32 v0, 0x80, v5
	v_xad_u32 v90, v0, v4, v6
	ds_read_b64_tr_b16 v[0:1], v90
	ds_read_b64_tr_b16 v[2:3], v90 offset:2048
	v_cvt_pk_bf16_f32 v148, v21, v22
	v_cvt_pk_bf16_f32 v149, v23, v24
	v_cvt_pk_bf16_f32 v67, v7, v8
	ds_bpermute_b32 v89, v174, v88
	s_waitcnt lgkmcnt(1)
	v_mfma_f32_32x32x16_bf16 v[16:31], v[0:3], v[166:169], 0
	v_or_b32_e32 v0, 0xc0, v5
	v_xad_u32 v91, v0, v4, v6
	ds_read_b64_tr_b16 v[0:1], v91
	ds_read_b64_tr_b16 v[2:3], v91 offset:2048
	ds_read_b64_tr_b16 v[94:95], v92 offset:4096
	ds_read_b64_tr_b16 v[96:97], v92 offset:6144
	s_waitcnt lgkmcnt(0)
	v_mfma_f32_32x32x16_bf16 v[48:63], v[94:97], v[162:165], v[48:63]
	ds_read_b64_tr_b16 v[94:95], v93 offset:4096
	ds_read_b64_tr_b16 v[96:97], v93 offset:6144
	s_waitcnt lgkmcnt(0)
	v_mfma_f32_32x32x16_bf16 v[32:47], v[94:97], v[162:165], v[32:47]
	ds_read_b64_tr_b16 v[94:95], v90 offset:4096
	ds_read_b64_tr_b16 v[96:97], v90 offset:6144
	v_mfma_f32_32x32x16_bf16 v[0:15], v[0:3], v[166:169], 0
	s_waitcnt lgkmcnt(0)
	v_mfma_f32_32x32x16_bf16 v[16:31], v[94:97], v[162:165], v[16:31]
	ds_read_b64_tr_b16 v[94:95], v91 offset:4096
	ds_read_b64_tr_b16 v[96:97], v91 offset:6144
	s_waitcnt lgkmcnt(0)
	v_mfma_f32_32x32x16_bf16 v[0:15], v[94:97], v[162:165], v[0:15]
	ds_read_b64_tr_b16 v[94:95], v92 offset:8192
	ds_read_b64_tr_b16 v[96:97], v92 offset:10240
	s_waitcnt lgkmcnt(0)
	v_mfma_f32_32x32x16_bf16 v[48:63], v[94:97], v[158:161], v[48:63]
	ds_read_b64_tr_b16 v[94:95], v93 offset:8192
	ds_read_b64_tr_b16 v[96:97], v93 offset:10240
	s_waitcnt lgkmcnt(0)
	v_mfma_f32_32x32x16_bf16 v[32:47], v[94:97], v[158:161], v[32:47]
	ds_read_b64_tr_b16 v[94:95], v90 offset:8192
	ds_read_b64_tr_b16 v[96:97], v90 offset:10240
	s_waitcnt lgkmcnt(0)
	v_mfma_f32_32x32x16_bf16 v[16:31], v[94:97], v[158:161], v[16:31]
	ds_read_b64_tr_b16 v[94:95], v91 offset:8192
	ds_read_b64_tr_b16 v[96:97], v91 offset:10240
	s_waitcnt lgkmcnt(0)
	v_mfma_f32_32x32x16_bf16 v[0:15], v[94:97], v[158:161], v[0:15]
	ds_read_b64_tr_b16 v[94:95], v92 offset:12288
	ds_read_b64_tr_b16 v[96:97], v92 offset:14336
	s_waitcnt lgkmcnt(0)
	v_mfma_f32_32x32x16_bf16 v[48:63], v[94:97], v[154:157], v[48:63]
	ds_read_b64_tr_b16 v[94:95], v93 offset:12288
	ds_read_b64_tr_b16 v[96:97], v93 offset:14336
	s_waitcnt lgkmcnt(0)
	v_mfma_f32_32x32x16_bf16 v[32:47], v[94:97], v[154:157], v[32:47]
	ds_read_b64_tr_b16 v[94:95], v90 offset:12288
	ds_read_b64_tr_b16 v[96:97], v90 offset:14336
	s_waitcnt lgkmcnt(0)
	v_mfma_f32_32x32x16_bf16 v[16:31], v[94:97], v[154:157], v[16:31]
	ds_read_b64_tr_b16 v[94:95], v91 offset:12288
	ds_read_b64_tr_b16 v[96:97], v91 offset:14336
	s_waitcnt lgkmcnt(0)
	v_mfma_f32_32x32x16_bf16 v[0:15], v[94:97], v[154:157], v[0:15]
	ds_read_b64_tr_b16 v[94:95], v92 offset:16384
	ds_read_b64_tr_b16 v[96:97], v92 offset:18432
	s_waitcnt lgkmcnt(0)
	v_mfma_f32_32x32x16_bf16 v[48:63], v[94:97], v[150:153], v[48:63]
	ds_read_b64_tr_b16 v[94:95], v93 offset:16384
	ds_read_b64_tr_b16 v[96:97], v93 offset:18432
	s_waitcnt lgkmcnt(0)
	v_mfma_f32_32x32x16_bf16 v[32:47], v[94:97], v[150:153], v[32:47]
	ds_read_b64_tr_b16 v[94:95], v90 offset:16384
	ds_read_b64_tr_b16 v[96:97], v90 offset:18432
	s_waitcnt lgkmcnt(0)
	v_mfma_f32_32x32x16_bf16 v[16:31], v[94:97], v[150:153], v[16:31]
	ds_read_b64_tr_b16 v[94:95], v91 offset:16384
	ds_read_b64_tr_b16 v[96:97], v91 offset:18432
	s_waitcnt lgkmcnt(0)
	v_mfma_f32_32x32x16_bf16 v[0:15], v[94:97], v[150:153], v[0:15]
	ds_read_b64_tr_b16 v[94:95], v92 offset:20480
	ds_read_b64_tr_b16 v[96:97], v92 offset:22528
	s_waitcnt lgkmcnt(0)
	v_mfma_f32_32x32x16_bf16 v[48:63], v[94:97], v[146:149], v[48:63]
	ds_read_b64_tr_b16 v[94:95], v93 offset:20480
	ds_read_b64_tr_b16 v[96:97], v93 offset:22528
	s_waitcnt lgkmcnt(0)
	v_mfma_f32_32x32x16_bf16 v[32:47], v[94:97], v[146:149], v[32:47]
	ds_read_b64_tr_b16 v[94:95], v90 offset:20480
	ds_read_b64_tr_b16 v[96:97], v90 offset:22528
	s_waitcnt lgkmcnt(0)
	v_mfma_f32_32x32x16_bf16 v[16:31], v[94:97], v[146:149], v[16:31]
	ds_read_b64_tr_b16 v[94:95], v91 offset:20480
	ds_read_b64_tr_b16 v[96:97], v91 offset:22528
	s_waitcnt lgkmcnt(0)
	v_mfma_f32_32x32x16_bf16 v[0:15], v[94:97], v[146:149], v[0:15]
	ds_read_b64_tr_b16 v[94:95], v92 offset:24576
	ds_read_b64_tr_b16 v[96:97], v92 offset:26624
	s_waitcnt lgkmcnt(0)
	v_mfma_f32_32x32x16_bf16 v[48:63], v[94:97], v[142:145], v[48:63]
	ds_read_b64_tr_b16 v[94:95], v93 offset:24576
	ds_read_b64_tr_b16 v[96:97], v93 offset:26624
	s_waitcnt lgkmcnt(0)
	v_mfma_f32_32x32x16_bf16 v[32:47], v[94:97], v[142:145], v[32:47]
	ds_read_b64_tr_b16 v[94:95], v90 offset:24576
	ds_read_b64_tr_b16 v[96:97], v90 offset:26624
	s_waitcnt lgkmcnt(0)
	v_mfma_f32_32x32x16_bf16 v[16:31], v[94:97], v[142:145], v[16:31]
	ds_read_b64_tr_b16 v[94:95], v91 offset:24576
	ds_read_b64_tr_b16 v[96:97], v91 offset:26624
	s_waitcnt lgkmcnt(0)
	v_mfma_f32_32x32x16_bf16 v[0:15], v[94:97], v[142:145], v[0:15]
	ds_read_b64_tr_b16 v[94:95], v92 offset:28672
	ds_read_b64_tr_b16 v[96:97], v92 offset:30720
	s_waitcnt lgkmcnt(0)
	v_mfma_f32_32x32x16_bf16 v[48:63], v[94:97], v[138:141], v[48:63]
	ds_read_b64_tr_b16 v[94:95], v93 offset:28672
	ds_read_b64_tr_b16 v[96:97], v93 offset:30720
	s_waitcnt lgkmcnt(0)
	v_mfma_f32_32x32x16_bf16 v[32:47], v[94:97], v[138:141], v[32:47]
	ds_read_b64_tr_b16 v[94:95], v90 offset:28672
	ds_read_b64_tr_b16 v[96:97], v90 offset:30720
	s_waitcnt lgkmcnt(0)
	v_mfma_f32_32x32x16_bf16 v[16:31], v[94:97], v[138:141], v[16:31]
	ds_read_b64_tr_b16 v[94:95], v91 offset:28672
	ds_read_b64_tr_b16 v[96:97], v91 offset:30720
	s_waitcnt lgkmcnt(0)
	v_mfma_f32_32x32x16_bf16 v[0:15], v[94:97], v[138:141], v[0:15]
	ds_read_b64_tr_b16 v[94:95], v92 offset:32768
	ds_read_b64_tr_b16 v[96:97], v92 offset:34816
	s_waitcnt lgkmcnt(0)
	v_mfma_f32_32x32x16_bf16 v[48:63], v[94:97], v[134:137], v[48:63]
	ds_read_b64_tr_b16 v[94:95], v93 offset:32768
	ds_read_b64_tr_b16 v[96:97], v93 offset:34816
	s_waitcnt lgkmcnt(0)
	v_mfma_f32_32x32x16_bf16 v[32:47], v[94:97], v[134:137], v[32:47]
	ds_read_b64_tr_b16 v[94:95], v90 offset:32768
	ds_read_b64_tr_b16 v[96:97], v90 offset:34816
	s_waitcnt lgkmcnt(0)
	v_mfma_f32_32x32x16_bf16 v[16:31], v[94:97], v[134:137], v[16:31]
	ds_read_b64_tr_b16 v[94:95], v91 offset:32768
	ds_read_b64_tr_b16 v[96:97], v91 offset:34816
	s_waitcnt lgkmcnt(0)
	v_mfma_f32_32x32x16_bf16 v[0:15], v[94:97], v[134:137], v[0:15]
	ds_read_b64_tr_b16 v[94:95], v92 offset:36864
	ds_read_b64_tr_b16 v[96:97], v92 offset:38912
	s_waitcnt lgkmcnt(0)
	v_mfma_f32_32x32x16_bf16 v[48:63], v[94:97], v[130:133], v[48:63]
	ds_read_b64_tr_b16 v[94:95], v93 offset:36864
	ds_read_b64_tr_b16 v[96:97], v93 offset:38912
	s_waitcnt lgkmcnt(0)
	v_mfma_f32_32x32x16_bf16 v[32:47], v[94:97], v[130:133], v[32:47]
	ds_read_b64_tr_b16 v[94:95], v90 offset:36864
	ds_read_b64_tr_b16 v[96:97], v90 offset:38912
	s_waitcnt lgkmcnt(0)
	v_mfma_f32_32x32x16_bf16 v[16:31], v[94:97], v[130:133], v[16:31]
	ds_read_b64_tr_b16 v[94:95], v91 offset:36864
	ds_read_b64_tr_b16 v[96:97], v91 offset:38912
	s_waitcnt lgkmcnt(0)
	v_mfma_f32_32x32x16_bf16 v[0:15], v[94:97], v[130:133], v[0:15]
	ds_read_b64_tr_b16 v[94:95], v92 offset:40960
	ds_read_b64_tr_b16 v[96:97], v92 offset:43008
	s_waitcnt lgkmcnt(0)
	v_mfma_f32_32x32x16_bf16 v[48:63], v[94:97], v[84:87], v[48:63]
	ds_read_b64_tr_b16 v[94:95], v93 offset:40960
	ds_read_b64_tr_b16 v[96:97], v93 offset:43008
	s_waitcnt lgkmcnt(0)
	v_mfma_f32_32x32x16_bf16 v[32:47], v[94:97], v[84:87], v[32:47]
	ds_read_b64_tr_b16 v[94:95], v90 offset:40960
	ds_read_b64_tr_b16 v[96:97], v90 offset:43008
	s_waitcnt lgkmcnt(0)
	v_mfma_f32_32x32x16_bf16 v[16:31], v[94:97], v[84:87], v[16:31]
	ds_read_b64_tr_b16 v[94:95], v91 offset:40960
	ds_read_b64_tr_b16 v[96:97], v91 offset:43008
	s_waitcnt lgkmcnt(0)
	v_mfma_f32_32x32x16_bf16 v[0:15], v[94:97], v[84:87], v[0:15]
	ds_read_b64_tr_b16 v[84:85], v92 offset:45056
	ds_read_b64_tr_b16 v[86:87], v92 offset:47104
	s_waitcnt lgkmcnt(0)
	v_mfma_f32_32x32x16_bf16 v[48:63], v[84:87], v[80:83], v[48:63]
	ds_read_b64_tr_b16 v[84:85], v93 offset:45056
	ds_read_b64_tr_b16 v[86:87], v93 offset:47104
	s_waitcnt lgkmcnt(0)
	v_mfma_f32_32x32x16_bf16 v[32:47], v[84:87], v[80:83], v[32:47]
	ds_read_b64_tr_b16 v[84:85], v90 offset:45056
	ds_read_b64_tr_b16 v[86:87], v90 offset:47104
	s_waitcnt lgkmcnt(0)
	v_mfma_f32_32x32x16_bf16 v[16:31], v[84:87], v[80:83], v[16:31]
	ds_read_b64_tr_b16 v[84:85], v91 offset:45056
	ds_read_b64_tr_b16 v[86:87], v91 offset:47104
	s_waitcnt lgkmcnt(0)
	v_mfma_f32_32x32x16_bf16 v[0:15], v[84:87], v[80:83], v[0:15]
	ds_read_b64_tr_b16 v[80:81], v92 offset:49152
	ds_read_b64_tr_b16 v[82:83], v92 offset:51200
	s_waitcnt lgkmcnt(0)
	v_mfma_f32_32x32x16_bf16 v[48:63], v[80:83], v[76:79], v[48:63]
	ds_read_b64_tr_b16 v[80:81], v93 offset:49152
	ds_read_b64_tr_b16 v[82:83], v93 offset:51200
	s_waitcnt lgkmcnt(0)
	v_mfma_f32_32x32x16_bf16 v[32:47], v[80:83], v[76:79], v[32:47]
	ds_read_b64_tr_b16 v[80:81], v90 offset:49152
	ds_read_b64_tr_b16 v[82:83], v90 offset:51200
	s_waitcnt lgkmcnt(0)
	v_mfma_f32_32x32x16_bf16 v[16:31], v[80:83], v[76:79], v[16:31]
	ds_read_b64_tr_b16 v[80:81], v91 offset:49152
	ds_read_b64_tr_b16 v[82:83], v91 offset:51200
	s_waitcnt lgkmcnt(0)
	v_mfma_f32_32x32x16_bf16 v[0:15], v[80:83], v[76:79], v[0:15]
	ds_read_b64_tr_b16 v[76:77], v92 offset:53248
	ds_read_b64_tr_b16 v[78:79], v92 offset:55296
	s_waitcnt lgkmcnt(0)
	v_mfma_f32_32x32x16_bf16 v[48:63], v[76:79], v[68:71], v[48:63]
	ds_read_b64_tr_b16 v[76:77], v93 offset:53248
	ds_read_b64_tr_b16 v[78:79], v93 offset:55296
	s_waitcnt lgkmcnt(0)
	v_mfma_f32_32x32x16_bf16 v[32:47], v[76:79], v[68:71], v[32:47]
	ds_read_b64_tr_b16 v[76:77], v90 offset:53248
	ds_read_b64_tr_b16 v[78:79], v90 offset:55296
	s_waitcnt lgkmcnt(0)
	v_mfma_f32_32x32x16_bf16 v[16:31], v[76:79], v[68:71], v[16:31]
	ds_read_b64_tr_b16 v[76:77], v91 offset:53248
	ds_read_b64_tr_b16 v[78:79], v91 offset:55296
	s_waitcnt lgkmcnt(0)
	v_mfma_f32_32x32x16_bf16 v[0:15], v[76:79], v[68:71], v[0:15]
	ds_read_b64_tr_b16 v[68:69], v92 offset:57344
	ds_read_b64_tr_b16 v[70:71], v92 offset:59392
	s_waitcnt lgkmcnt(0)
	v_mfma_f32_32x32x16_bf16 v[48:63], v[68:71], v[72:75], v[48:63]
	ds_read_b64_tr_b16 v[68:69], v93 offset:57344
	ds_read_b64_tr_b16 v[70:71], v93 offset:59392
	s_waitcnt lgkmcnt(0)
	v_mfma_f32_32x32x16_bf16 v[32:47], v[68:71], v[72:75], v[32:47]
	ds_read_b64_tr_b16 v[68:69], v90 offset:57344
	ds_read_b64_tr_b16 v[70:71], v90 offset:59392
	s_waitcnt lgkmcnt(0)
	v_mfma_f32_32x32x16_bf16 v[16:31], v[68:71], v[72:75], v[16:31]
	ds_read_b64_tr_b16 v[68:69], v91 offset:57344
	ds_read_b64_tr_b16 v[70:71], v91 offset:59392
	s_waitcnt lgkmcnt(0)
	v_mfma_f32_32x32x16_bf16 v[0:15], v[68:71], v[72:75], v[0:15]
	ds_read_b64_tr_b16 v[68:69], v92 offset:61440
	ds_read_b64_tr_b16 v[70:71], v92 offset:63488
	s_waitcnt lgkmcnt(0)
	v_mfma_f32_32x32x16_bf16 v[48:63], v[68:71], v[64:67], v[48:63]
	ds_read_b64_tr_b16 v[68:69], v93 offset:61440
	ds_read_b64_tr_b16 v[70:71], v93 offset:63488
	s_waitcnt lgkmcnt(0)
	v_mfma_f32_32x32x16_bf16 v[32:47], v[68:71], v[64:67], v[32:47]
	ds_read_b64_tr_b16 v[68:69], v90 offset:61440
	ds_read_b64_tr_b16 v[70:71], v90 offset:63488
	s_waitcnt lgkmcnt(0)
	v_mfma_f32_32x32x16_bf16 v[16:31], v[68:71], v[64:67], v[16:31]
	ds_read_b64_tr_b16 v[68:69], v91 offset:61440
	ds_read_b64_tr_b16 v[70:71], v91 offset:63488
	s_waitcnt lgkmcnt(0)
	v_mfma_f32_32x32x16_bf16 v[0:15], v[68:71], v[64:67], v[0:15]
	v_add_f32_e32 v64, v88, v89
	v_div_scale_f32 v65, s[4:5], v64, v64, 1.0
	v_rcp_f32_e32 v66, v65
	v_readlane_b32 s4, v237, 38
	s_add_i32 s9, s9, s4
	v_readlane_b32 s4, v237, 58
	v_fma_f32 v67, -v65, v66, 1.0
	v_fmac_f32_e32 v66, v67, v66
	v_div_scale_f32 v67, vcc, 1.0, v64, 1.0
	v_mul_f32_e32 v68, v67, v66
	v_fma_f32 v69, -v65, v68, v67
	v_fmac_f32_e32 v68, v69, v66
	v_fma_f32 v65, -v65, v68, v67
	v_div_fmas_f32 v65, v65, v66, v68
	v_div_fixup_f32 v64, v65, v64, 1.0
	v_pk_mul_f32 v[48:49], v[64:65], v[48:49] op_sel_hi:[0,1]
	v_pk_mul_f32 v[50:51], v[64:65], v[50:51] op_sel_hi:[0,1]
	v_pk_mul_f32 v[32:33], v[64:65], v[32:33] op_sel_hi:[0,1]
	v_pk_mul_f32 v[34:35], v[64:65], v[34:35] op_sel_hi:[0,1]
	v_pk_mul_f32 v[16:17], v[64:65], v[16:17] op_sel_hi:[0,1]
	v_pk_mul_f32 v[18:19], v[64:65], v[18:19] op_sel_hi:[0,1]
	v_pk_mul_f32 v[0:1], v[64:65], v[0:1] op_sel_hi:[0,1]
	v_pk_mul_f32 v[2:3], v[64:65], v[2:3] op_sel_hi:[0,1]
	v_lshl_add_u64 v[66:67], v[170:171], 0, v[128:129]
	v_cvt_pk_bf16_f32 v48, v48, v49
	v_cvt_pk_bf16_f32 v49, v50, v51
	v_cvt_pk_bf16_f32 v32, v32, v33
	v_cvt_pk_bf16_f32 v33, v34, v35
	v_cvt_pk_bf16_f32 v16, v16, v17
	v_cvt_pk_bf16_f32 v17, v18, v19
	v_cvt_pk_bf16_f32 v0, v0, v1
	v_cvt_pk_bf16_f32 v1, v2, v3
	global_store_dwordx2 v[66:67], v[48:49], off
	v_pk_mul_f32 v[48:49], v[64:65], v[52:53] op_sel_hi:[0,1]
	v_pk_mul_f32 v[50:51], v[64:65], v[54:55] op_sel_hi:[0,1]
	global_store_dwordx2 v[66:67], v[32:33], off offset:64
	v_pk_mul_f32 v[32:33], v[64:65], v[36:37] op_sel_hi:[0,1]
	v_pk_mul_f32 v[34:35], v[64:65], v[38:39] op_sel_hi:[0,1]
	global_store_dwordx2 v[66:67], v[16:17], off offset:128
	v_pk_mul_f32 v[16:17], v[64:65], v[20:21] op_sel_hi:[0,1]
	v_pk_mul_f32 v[18:19], v[64:65], v[22:23] op_sel_hi:[0,1]
	global_store_dwordx2 v[66:67], v[0:1], off offset:192
	v_pk_mul_f32 v[0:1], v[64:65], v[4:5] op_sel_hi:[0,1]
	v_pk_mul_f32 v[2:3], v[64:65], v[6:7] op_sel_hi:[0,1]
	v_cvt_pk_bf16_f32 v48, v48, v49
	v_cvt_pk_bf16_f32 v49, v50, v51
	v_cvt_pk_bf16_f32 v32, v32, v33
	v_cvt_pk_bf16_f32 v33, v34, v35
	v_cvt_pk_bf16_f32 v16, v16, v17
	v_cvt_pk_bf16_f32 v17, v18, v19
	v_cvt_pk_bf16_f32 v0, v0, v1
	v_cvt_pk_bf16_f32 v1, v2, v3
	global_store_dwordx2 v[66:67], v[48:49], off offset:16
	v_pk_mul_f32 v[48:49], v[64:65], v[56:57] op_sel_hi:[0,1]
	v_pk_mul_f32 v[50:51], v[64:65], v[58:59] op_sel_hi:[0,1]
	global_store_dwordx2 v[66:67], v[32:33], off offset:80
	v_pk_mul_f32 v[32:33], v[64:65], v[40:41] op_sel_hi:[0,1]
	v_pk_mul_f32 v[34:35], v[64:65], v[42:43] op_sel_hi:[0,1]
	global_store_dwordx2 v[66:67], v[16:17], off offset:144
	v_pk_mul_f32 v[16:17], v[64:65], v[24:25] op_sel_hi:[0,1]
	v_pk_mul_f32 v[18:19], v[64:65], v[26:27] op_sel_hi:[0,1]
	global_store_dwordx2 v[66:67], v[0:1], off offset:208
	v_pk_mul_f32 v[0:1], v[64:65], v[8:9] op_sel_hi:[0,1]
	v_pk_mul_f32 v[2:3], v[64:65], v[10:11] op_sel_hi:[0,1]
	v_cvt_pk_bf16_f32 v48, v48, v49
	v_cvt_pk_bf16_f32 v49, v50, v51
	v_cvt_pk_bf16_f32 v32, v32, v33
	v_cvt_pk_bf16_f32 v33, v34, v35
	v_cvt_pk_bf16_f32 v16, v16, v17
	v_cvt_pk_bf16_f32 v17, v18, v19
	v_cvt_pk_bf16_f32 v0, v0, v1
	v_cvt_pk_bf16_f32 v1, v2, v3
	global_store_dwordx2 v[66:67], v[48:49], off offset:32
	v_pk_mul_f32 v[48:49], v[64:65], v[60:61] op_sel_hi:[0,1]
	v_pk_mul_f32 v[50:51], v[64:65], v[62:63] op_sel_hi:[0,1]
	global_store_dwordx2 v[66:67], v[32:33], off offset:96
	v_pk_mul_f32 v[32:33], v[64:65], v[44:45] op_sel_hi:[0,1]
	v_pk_mul_f32 v[34:35], v[64:65], v[46:47] op_sel_hi:[0,1]
	global_store_dwordx2 v[66:67], v[16:17], off offset:160
	v_pk_mul_f32 v[16:17], v[64:65], v[28:29] op_sel_hi:[0,1]
	v_pk_mul_f32 v[18:19], v[64:65], v[30:31] op_sel_hi:[0,1]
	global_store_dwordx2 v[66:67], v[0:1], off offset:224
	v_pk_mul_f32 v[0:1], v[64:65], v[12:13] op_sel_hi:[0,1]
	v_pk_mul_f32 v[2:3], v[64:65], v[14:15] op_sel_hi:[0,1]
	s_add_i32 s8, s8, s4
	v_cvt_pk_bf16_f32 v48, v48, v49
	v_cvt_pk_bf16_f32 v49, v50, v51
	v_cvt_pk_bf16_f32 v32, v32, v33
	v_cvt_pk_bf16_f32 v33, v34, v35
	v_cvt_pk_bf16_f32 v16, v16, v17
	v_cvt_pk_bf16_f32 v17, v18, v19
	v_cvt_pk_bf16_f32 v0, v0, v1
	v_cvt_pk_bf16_f32 v1, v2, v3
	s_cmpk_gt_i32 s10, 0x7f
	global_store_dwordx2 v[66:67], v[48:49], off offset:48
	global_store_dwordx2 v[66:67], v[32:33], off offset:112
	global_store_dwordx2 v[66:67], v[16:17], off offset:176
	global_store_dwordx2 v[66:67], v[0:1], off offset:240
	s_cbranch_scc1 .LBB0_1308
.LBB0_1292:
	s_ashr_i32 s4, s10, 5
	s_lshl_b32 s6, s4, 8
	s_ashr_i32 s7, s6, 31
	s_lshl_b64 s[6:7], s[6:7], 11
	s_add_u32 s5, s0, s6
	s_addc_u32 s7, s1, s7
	s_and_b32 s6, s9, 0x180
	v_mov_b32_e32 v15, v190
	s_lshl_b32 s22, s6, 1
	v_mov_b32_e32 v172, v190
	s_add_u32 s6, s5, s22
	s_addc_u32 s7, s7, 0
	v_and_b32_e32 v14, 15, v172
	v_ashrrev_i32_e32 v12, 4, v172
	v_lshlrev_b32_e32 v128, 4, v14
	v_lshl_add_u64 v[10:11], s[6:7], 0, v[128:129]
	v_cmp_lt_i32_e32 vcc, -1, v12
	v_mov_b32_e32 v0, 0
	v_mov_b32_e32 v2, 0
	v_mov_b32_e32 v3, 0
	v_mov_b32_e32 v4, 0
	v_mov_b32_e32 v5, 0
	v_mov_b32_e32 v6, 0
	v_mov_b32_e32 v7, 0
	v_mov_b32_e32 v8, 0
	v_mov_b32_e32 v9, 0
	v_mov_b32_e32 v18, 0
	v_mov_b32_e32 v19, 0
	v_mov_b32_e32 v20, 0
	v_mov_b32_e32 v21, 0
	v_mov_b32_e32 v22, 0
	v_mov_b32_e32 v23, 0
	v_mov_b32_e32 v24, 0
	v_mov_b32_e32 v25, 0
	v_mov_b32_e32 v26, 0
	v_mov_b32_e32 v27, 0
	v_mov_b32_e32 v28, 0
	v_mov_b32_e32 v29, 0
	v_mov_b32_e32 v30, 0
	v_mov_b32_e32 v31, 0
	v_mov_b32_e32 v32, 0
	v_mov_b32_e32 v33, 0
	v_mov_b32_e32 v34, 0
	v_mov_b32_e32 v35, 0
	v_mov_b32_e32 v36, 0
	v_mov_b32_e32 v37, 0
	v_mov_b32_e32 v38, 0
	v_mov_b32_e32 v39, 0
	v_mov_b32_e32 v40, 0
	v_mov_b32_e32 v41, 0
	v_mov_b32_e32 v42, 0
	v_mov_b32_e32 v43, 0
	v_mov_b32_e32 v44, 0
	v_mov_b32_e32 v45, 0
	v_mov_b32_e32 v46, 0
	v_mov_b32_e32 v47, 0
	v_mov_b32_e32 v48, 0
	v_mov_b32_e32 v49, 0
	v_mov_b32_e32 v50, 0
	v_mov_b32_e32 v51, 0
	v_mov_b32_e32 v52, 0
	v_mov_b32_e32 v53, 0
	v_mov_b32_e32 v54, 0
	v_mov_b32_e32 v55, 0
	v_mov_b32_e32 v56, 0
	v_mov_b32_e32 v57, 0
	v_mov_b32_e32 v58, 0
	v_mov_b32_e32 v59, 0
	v_mov_b32_e32 v60, 0
	v_mov_b32_e32 v61, 0
	v_mov_b32_e32 v62, 0
	v_mov_b32_e32 v63, 0
	v_mov_b32_e32 v64, 0
	v_mov_b32_e32 v65, 0
	v_mov_b32_e32 v66, 0
	v_mov_b32_e32 v67, 0
	v_mov_b32_e32 v68, 0
	v_mov_b32_e32 v69, 0
	v_mov_b32_e32 v70, 0
	v_mov_b32_e32 v71, 0
	v_mov_b32_e32 v72, 0
	v_mov_b32_e32 v73, 0
	v_mov_b32_e32 v74, 0
	v_mov_b32_e32 v75, 0
	v_mov_b32_e32 v76, 0
	v_mov_b32_e32 v77, 0
	v_mov_b32_e32 v78, 0
	v_mov_b32_e32 v79, 0
	v_mov_b32_e32 v80, 0
	v_mov_b32_e32 v81, 0
	v_mov_b32_e32 v84, v12
	v_mov_b32_e32 v85, v129
	v_cmp_lt_i32_e32 vcc, -1, v84
	s_and_saveexec_b64 s[6:7], vcc
	v_lshlrev_b64 v[82:83], 11, v[84:85]
	v_lshl_add_u64 v[82:83], v[10:11], 0, v[82:83]
	global_load_dwordx4 v[18:21], v[82:83], off
	global_load_dwordx4 v[22:25], v[82:83], off offset:1024
	s_or_b64 exec, exec, s[6:7]
	v_add_u32_e32 v84, 32, v12
	v_mov_b32_e32 v85, v129
	v_cmp_lt_i32_e32 vcc, -1, v84
	s_and_saveexec_b64 s[6:7], vcc
	v_lshlrev_b64 v[82:83], 11, v[84:85]
	v_lshl_add_u64 v[82:83], v[10:11], 0, v[82:83]
	global_load_dwordx4 v[26:29], v[82:83], off
	global_load_dwordx4 v[30:33], v[82:83], off offset:1024
	s_or_b64 exec, exec, s[6:7]
	v_add_u32_e32 v84, 64, v12
	v_mov_b32_e32 v85, v129
	v_cmp_lt_i32_e32 vcc, -1, v84
	s_and_saveexec_b64 s[6:7], vcc
	v_lshlrev_b64 v[82:83], 11, v[84:85]
	v_lshl_add_u64 v[82:83], v[10:11], 0, v[82:83]
	global_load_dwordx4 v[34:37], v[82:83], off
	global_load_dwordx4 v[38:41], v[82:83], off offset:1024
	s_or_b64 exec, exec, s[6:7]
	v_add_u32_e32 v84, 96, v12
	v_mov_b32_e32 v85, v129
	v_cmp_lt_i32_e32 vcc, -1, v84
	s_and_saveexec_b64 s[6:7], vcc
	v_lshlrev_b64 v[82:83], 11, v[84:85]
	v_lshl_add_u64 v[82:83], v[10:11], 0, v[82:83]
	global_load_dwordx4 v[42:45], v[82:83], off
	global_load_dwordx4 v[46:49], v[82:83], off offset:1024
	s_or_b64 exec, exec, s[6:7]
	v_add_u32_e32 v84, 128, v12
	v_mov_b32_e32 v85, v129
	v_cmp_lt_i32_e32 vcc, -1, v84
	s_and_saveexec_b64 s[6:7], vcc
	v_lshlrev_b64 v[82:83], 11, v[84:85]
	v_lshl_add_u64 v[82:83], v[10:11], 0, v[82:83]
	global_load_dwordx4 v[50:53], v[82:83], off
	global_load_dwordx4 v[54:57], v[82:83], off offset:1024
	s_or_b64 exec, exec, s[6:7]
	v_add_u32_e32 v84, 160, v12
	v_mov_b32_e32 v85, v129
	v_cmp_lt_i32_e32 vcc, -1, v84
	s_and_saveexec_b64 s[6:7], vcc
	v_lshlrev_b64 v[82:83], 11, v[84:85]
	v_lshl_add_u64 v[82:83], v[10:11], 0, v[82:83]
	global_load_dwordx4 v[58:61], v[82:83], off
	global_load_dwordx4 v[62:65], v[82:83], off offset:1024
	s_or_b64 exec, exec, s[6:7]
	v_add_u32_e32 v84, 192, v12
	v_mov_b32_e32 v85, v129
	v_cmp_lt_i32_e32 vcc, -1, v84
	s_and_saveexec_b64 s[6:7], vcc
	v_lshlrev_b64 v[82:83], 11, v[84:85]
	v_lshl_add_u64 v[82:83], v[10:11], 0, v[82:83]
	global_load_dwordx4 v[66:69], v[82:83], off
	global_load_dwordx4 v[70:73], v[82:83], off offset:1024
	s_or_b64 exec, exec, s[6:7]
	v_add_u32_e32 v84, 224, v12
	v_mov_b32_e32 v85, v129
	v_cmp_lt_i32_e32 vcc, -1, v84
	s_and_saveexec_b64 s[6:7], vcc
	v_lshlrev_b64 v[82:83], 11, v[84:85]
	v_lshl_add_u64 v[82:83], v[10:11], 0, v[82:83]
	global_load_dwordx4 v[74:77], v[82:83], off
	global_load_dwordx4 v[78:81], v[82:83], off offset:1024
	s_or_b64 exec, exec, s[6:7]
	s_barrier
	v_xor_b32_e32 v1, v12, v172
	v_lshlrev_b32_e32 v1, 4, v1
	v_and_b32_e32 v1, 0xf0, v1
	v_add_u32_e32 v13, 0, v1
	v_lshrrev_b32_e32 v1, 1, v14
	v_lshlrev_b32_e32 v16, 1, v12
	v_bitop3_b32 v1, v16, v1, 6 bitop3:0x6c
	v_lshlrev_b32_e32 v16, 4, v172
	v_lshlrev_b32_e32 v1, 5, v1
	v_and_b32_e32 v16, 16, v16
	s_add_i32 s11, 0, 0x10000
	v_add3_u32 v16, s11, v1, v16
	v_lshlrev_b32_e32 v1, 8, v12
	v_add_u32_e32 v17, v13, v1
	v_add_u32_e32 v1, v16, v1
	s_movk_i32 s5, 0xffdf
	s_waitcnt vmcnt(15)
	ds_write_b128 v17, v[18:21]
	s_waitcnt vmcnt(14)
	ds_write_b128 v1, v[22:25]
	v_add_u32_e32 v128, 32, v12
	v_cmp_lt_i32_e32 vcc, s5, v12
	v_mov_b32_e32 v1, 0
	v_mov_b32_e32 v2, 0
	v_mov_b32_e32 v3, 0
	v_mov_b32_e32 v4, 0
	v_mov_b32_e32 v5, 0
	v_mov_b32_e32 v6, 0
	v_mov_b32_e32 v7, 0
	v_lshlrev_b32_e32 v8, 8, v128
	v_add_u32_e32 v9, v13, v8
	s_waitcnt vmcnt(13)
	ds_write_b128 v9, v[26:29]
	v_add_u32_e32 v4, v16, v8
	s_movk_i32 s5, 0xffbf
	s_waitcnt vmcnt(12)
	ds_write_b128 v4, v[30:33]
	v_add_u32_e32 v128, 64, v12
	v_cmp_lt_i32_e32 vcc, s5, v12
	v_mov_b32_e32 v0, 0
	v_mov_b32_e32 v2, 0
	v_mov_b32_e32 v3, 0
	v_mov_b32_e32 v4, 0
	v_mov_b32_e32 v5, 0
	v_mov_b32_e32 v6, 0
	v_mov_b32_e32 v7, 0
	v_mov_b32_e32 v8, 0
	v_mov_b32_e32 v9, 0
	v_lshlrev_b32_e32 v1, 8, v128
	v_add_u32_e32 v17, v13, v1
	v_add_u32_e32 v1, v16, v1
	s_movk_i32 s5, 0xff9f
	s_waitcnt vmcnt(11)
	ds_write_b128 v17, v[34:37]
	s_waitcnt vmcnt(10)
	ds_write_b128 v1, v[38:41]
	v_add_u32_e32 v128, 0x60, v12
	v_cmp_lt_i32_e32 vcc, s5, v12
	v_mov_b32_e32 v1, 0
	v_mov_b32_e32 v2, 0
	v_mov_b32_e32 v3, 0
	v_mov_b32_e32 v4, 0
	v_mov_b32_e32 v5, 0
	v_mov_b32_e32 v6, 0
	v_mov_b32_e32 v7, 0
	v_lshlrev_b32_e32 v8, 8, v128
	v_add_u32_e32 v9, v13, v8
	s_waitcnt vmcnt(9)
	ds_write_b128 v9, v[42:45]
	v_add_u32_e32 v4, v16, v8
	s_movk_i32 s5, 0xff7f
	s_waitcnt vmcnt(8)
	ds_write_b128 v4, v[46:49]
	v_add_u32_e32 v128, 0x80, v12
	v_cmp_lt_i32_e32 vcc, s5, v12
	v_mov_b32_e32 v0, 0
	v_mov_b32_e32 v2, 0
	v_mov_b32_e32 v3, 0
	v_mov_b32_e32 v4, 0
	v_mov_b32_e32 v5, 0
	v_mov_b32_e32 v6, 0
	v_mov_b32_e32 v7, 0
	v_mov_b32_e32 v8, 0
	v_mov_b32_e32 v9, 0
	v_lshlrev_b32_e32 v1, 8, v128
	v_add_u32_e32 v17, v13, v1
	v_add_u32_e32 v1, v16, v1
	s_movk_i32 s5, 0xff5f
	s_waitcnt vmcnt(7)
	ds_write_b128 v17, v[50:53]
	s_waitcnt vmcnt(6)
	ds_write_b128 v1, v[54:57]
	v_add_u32_e32 v128, 0xa0, v12
	v_cmp_lt_i32_e32 vcc, s5, v12
	v_mov_b32_e32 v1, 0
	v_mov_b32_e32 v2, 0
	v_mov_b32_e32 v3, 0
	v_mov_b32_e32 v4, 0
	v_mov_b32_e32 v5, 0
	v_mov_b32_e32 v6, 0
	v_mov_b32_e32 v7, 0
	v_lshlrev_b32_e32 v8, 8, v128
	v_add_u32_e32 v9, v13, v8
	s_waitcnt vmcnt(5)
	ds_write_b128 v9, v[58:61]
	v_add_u32_e32 v4, v16, v8
	s_movk_i32 s5, 0xff3f
	s_waitcnt vmcnt(4)
	ds_write_b128 v4, v[62:65]
	v_add_u32_e32 v128, 0xc0, v12
	v_cmp_lt_i32_e32 vcc, s5, v12
	v_mov_b32_e32 v0, 0
	v_mov_b32_e32 v2, 0
	v_mov_b32_e32 v3, 0
	v_mov_b32_e32 v4, 0
	v_mov_b32_e32 v5, 0
	v_mov_b32_e32 v6, 0
	v_mov_b32_e32 v7, 0
	v_mov_b32_e32 v8, 0
	v_mov_b32_e32 v9, 0
	v_lshlrev_b32_e32 v1, 8, v128
	v_add_u32_e32 v17, v13, v1
	v_add_u32_e32 v1, v16, v1
	s_movk_i32 s5, 0xff1f
	s_waitcnt vmcnt(3)
	ds_write_b128 v17, v[66:69]
	s_waitcnt vmcnt(2)
	ds_write_b128 v1, v[70:73]
	v_add_u32_e32 v128, 0xe0, v12
	v_cmp_lt_i32_e32 vcc, s5, v12
	v_mov_b32_e32 v1, 0
	v_mov_b32_e32 v2, 0
	v_mov_b32_e32 v3, 0
	v_mov_b32_e32 v4, 0
	v_mov_b32_e32 v5, 0
	v_mov_b32_e32 v6, 0
	v_mov_b32_e32 v7, 0
	s_branch .LBB0_1291
